# SwiGLU epilogue (P2, P11): each row segment stored as soon as it is converted instead of eight stores at the end, so the next unit's counted waits do not sit behind fresh stores
# baseline (speedup 1.0000x reference)
; __device__ __forceinline__ unsigned pk2(float lo, float hi) { const f32x2c v = {lo, hi}; const bf16x2c b = __builtin_convertvector(v, bf16x2c); return __builtin_bit_cast(unsigned, b); }
; __device__ __forceinline__ float fast_sigmoid(float x) { return __builtin_amdgcn_rcpf(1.f + __expf(-x)); }
; __device__ __forceinline__ float silu_f(float x) { return x * fast_sigmoid(x); }
;     __device__ __forceinline__ void operator()(const f32x4 (&acc)[2][2][4][2], const pg8::Unit& u, int wr, int wc, int fr, int fq) const {
;         const int row0 = u.pm * 256 + wr * 64 + fr, col0 = u.pn * 128 + wc * 32 + 8 * fq;
; #pragma unroll
;         for (int ai = 0; ai < 2; ++ai)
; #pragma unroll
;             for (int m = 0; m < 4; ++m) {
;                 bf16_t* rowp = O + (size_t)(row0 + ai * 128 + m * 16) * ldc + col0;
;                 const f32x4 a0 = acc[ai][0][m][0], a1 = acc[ai][0][m][1], b0 = acc[ai][1][m][0], b1 = acc[ai][1][m][1];
;                 u32x4 w;
;                 w.x = pk2(silu_f(a0[0]) * b0[0], silu_f(a0[1]) * b0[1]); w.y = pk2(silu_f(a0[2]) * b0[2], silu_f(a0[3]) * b0[3]);
;                 w.z = pk2(silu_f(a1[0]) * b1[0], silu_f(a1[1]) * b1[1]); w.w = pk2(silu_f(a1[2]) * b1[2], silu_f(a1[3]) * b1[3]);
;                 *(u32x4*)rowp = w;
;             }
.LBB0_153:
	v_mul_f32_e32 v155, 0xbfb8aa3b, v124
	v_exp_f32_e32 v155, v155
	v_mul_f32_e32 v158, 0xbfb8aa3b, v125
	v_exp_f32_e32 v159, v158
	v_lshl_add_u32 v154, s28, 8, v148
	v_add_f32_e32 v155, 1.0, v155
	v_rcp_f32_e32 v158, v155
	v_add_f32_e32 v155, 1.0, v159
	v_mul_f32_e32 v159, 0xbfb8aa3b, v126
	v_exp_f32_e32 v160, v159
	v_mul_f32_e32 v159, 0xbfb8aa3b, v127
	v_exp_f32_e32 v161, v159
	v_rcp_f32_e32 v159, v155
	v_add_f32_e32 v155, 1.0, v160
	v_rcp_f32_e32 v160, v155
	v_add_f32_e32 v155, 1.0, v161
	v_rcp_f32_e32 v161, v155
	v_pk_mul_f32 v[124:125], v[124:125], v[158:159]
	v_lshl_add_u32 v144, s71, 7, v150
	v_pk_mul_f32 v[120:121], v[124:125], v[120:121]
	v_pk_mul_f32 v[124:125], v[126:127], v[160:161]
	v_cvt_pk_bf16_f32 v120, v120, v121
	v_mul_f32_e32 v121, 0xbfb8aa3b, v116
	v_pk_mul_f32 v[122:123], v[124:125], v[122:123]
	v_exp_f32_e32 v124, v121
	v_mul_f32_e32 v121, 0xbfb8aa3b, v117
	v_exp_f32_e32 v125, v121
	v_cvt_pk_bf16_f32 v121, v122, v123
	v_add_f32_e32 v122, 1.0, v124
	v_mul_f32_e32 v124, 0xbfb8aa3b, v118
	v_add_f32_e32 v123, 1.0, v125
	v_mul_f32_e32 v125, 0xbfb8aa3b, v119
	v_exp_f32_e32 v124, v124
	v_exp_f32_e32 v125, v125
	v_rcp_f32_e32 v122, v122
	v_rcp_f32_e32 v123, v123
	v_add_f32_e32 v124, 1.0, v124
	v_add_f32_e32 v125, 1.0, v125
	v_rcp_f32_e32 v124, v124
	v_rcp_f32_e32 v125, v125
	v_pk_mul_f32 v[116:117], v[116:117], v[122:123]
	v_ashrrev_i32_e32 v145, 31, v144
	v_pk_mul_f32 v[112:113], v[116:117], v[112:113]
	v_mul_f32_e32 v116, 0xbfb8aa3b, v110
	v_cvt_pk_bf16_f32 v122, v112, v113
	v_pk_mul_f32 v[112:113], v[118:119], v[124:125]
	v_mul_f32_e32 v117, 0xbfb8aa3b, v111
	v_pk_mul_f32 v[112:113], v[112:113], v[114:115]
	v_mul_f32_e32 v114, 0xbfb8aa3b, v108
	v_mul_f32_e32 v115, 0xbfb8aa3b, v109
	v_exp_f32_e32 v114, v114
	v_exp_f32_e32 v115, v115
	v_exp_f32_e32 v116, v116
	v_exp_f32_e32 v117, v117
	v_add_f32_e32 v114, 1.0, v114
	v_add_f32_e32 v115, 1.0, v115
	v_rcp_f32_e32 v114, v114
	v_rcp_f32_e32 v115, v115
	v_add_f32_e32 v116, 1.0, v116
	v_add_f32_e32 v117, 1.0, v117
	v_rcp_f32_e32 v116, v116
	v_rcp_f32_e32 v117, v117
	v_pk_mul_f32 v[108:109], v[108:109], v[114:115]
	s_cselect_b32 s98, 1, 0
	s_lshr_b32 s99, s28, 1
	s_and_b32 s100, s99, 7
	s_lshl_b32 s100, s100, 1
	s_bfe_u32 s101, s99, 0x10003
	s_or_b32 s100, s100, s101
	s_and_b32 s101, s99, 0x30
	s_or_b32 s100, s100, s101
	s_mul_i32 s100, s100, 0x300000
	s_mul_i32 s99, s99, 0x2c0000
	s_add_u32 s100, s100, 0xd000000
	s_sub_u32 s100, s100, s99
	s_add_u32 s100, s96, s100
	s_addc_u32 s101, s97, 0
	s_cmp_lg_u32 s98, 0
	v_mov_b64_e32 v[146:147], s[100:101]
	v_pk_mul_f32 v[104:105], v[108:109], v[104:105]
	v_pk_mul_f32 v[108:109], v[110:111], v[116:117]
	v_cvt_pk_bf16_f32 v104, v104, v105
	v_mul_f32_e32 v105, 0xbfb8aa3b, v100
	v_pk_mul_f32 v[106:107], v[108:109], v[106:107]
	v_exp_f32_e32 v108, v105
	v_mul_f32_e32 v105, 0xbfb8aa3b, v101
	v_exp_f32_e32 v109, v105
	v_cvt_pk_bf16_f32 v105, v106, v107
	v_add_f32_e32 v106, 1.0, v108
	v_mul_f32_e32 v108, 0xbfb8aa3b, v102
	v_add_f32_e32 v107, 1.0, v109
	v_mul_f32_e32 v109, 0xbfb8aa3b, v103
	v_exp_f32_e32 v108, v108
	v_exp_f32_e32 v109, v109
	v_rcp_f32_e32 v106, v106
	v_rcp_f32_e32 v107, v107
	v_add_f32_e32 v108, 1.0, v108
	v_add_f32_e32 v109, 1.0, v109
	v_rcp_f32_e32 v108, v108
	v_rcp_f32_e32 v109, v109
	v_pk_mul_f32 v[100:101], v[100:101], v[106:107]
	v_cvt_pk_bf16_f32 v123, v112, v113
	v_lshlrev_b64 v[144:145], 1, v[144:145]
	v_mad_i64_i32 v[156:157], s[30:31], v154, s70, v[146:147]
	v_lshl_add_u64 v[156:157], v[156:157], 0, v[144:145]
	global_store_dwordx4 v[156:157], v[120:123], off nt
	v_pk_mul_f32 v[96:97], v[100:101], v[96:97]
	v_mul_f32_e32 v100, 0xbfb8aa3b, v94
	v_cvt_pk_bf16_f32 v106, v96, v97
	v_pk_mul_f32 v[96:97], v[102:103], v[108:109]
	v_mul_f32_e32 v101, 0xbfb8aa3b, v95
	v_pk_mul_f32 v[96:97], v[96:97], v[98:99]
	v_mul_f32_e32 v98, 0xbfb8aa3b, v92
	v_mul_f32_e32 v99, 0xbfb8aa3b, v93
	v_exp_f32_e32 v98, v98
	v_exp_f32_e32 v99, v99
	v_exp_f32_e32 v100, v100
	v_exp_f32_e32 v101, v101
	v_add_f32_e32 v98, 1.0, v98
	v_add_f32_e32 v99, 1.0, v99
	v_rcp_f32_e32 v98, v98
	v_rcp_f32_e32 v99, v99
	v_add_f32_e32 v100, 1.0, v100
	v_add_f32_e32 v101, 1.0, v101
	v_rcp_f32_e32 v100, v100
	v_rcp_f32_e32 v101, v101
	v_pk_mul_f32 v[92:93], v[92:93], v[98:99]
	v_or_b32_e32 v112, 16, v154
	v_pk_mul_f32 v[88:89], v[92:93], v[88:89]
	v_pk_mul_f32 v[92:93], v[94:95], v[100:101]
	v_cvt_pk_bf16_f32 v88, v88, v89
	v_mul_f32_e32 v89, 0xbfb8aa3b, v84
	v_pk_mul_f32 v[90:91], v[92:93], v[90:91]
	v_exp_f32_e32 v92, v89
	v_mul_f32_e32 v89, 0xbfb8aa3b, v85
	v_exp_f32_e32 v93, v89
	v_cvt_pk_bf16_f32 v89, v90, v91
	v_add_f32_e32 v90, 1.0, v92
	v_mul_f32_e32 v92, 0xbfb8aa3b, v86
	v_add_f32_e32 v91, 1.0, v93
	v_mul_f32_e32 v93, 0xbfb8aa3b, v87
	v_exp_f32_e32 v92, v92
	v_exp_f32_e32 v93, v93
	v_rcp_f32_e32 v90, v90
	v_rcp_f32_e32 v91, v91
	v_add_f32_e32 v92, 1.0, v92
	v_add_f32_e32 v93, 1.0, v93
	v_rcp_f32_e32 v92, v92
	v_rcp_f32_e32 v93, v93
	v_pk_mul_f32 v[84:85], v[84:85], v[90:91]
	v_cvt_pk_bf16_f32 v107, v96, v97
	v_mad_i64_i32 v[112:113], s[30:31], v112, s70, v[146:147]
	v_lshl_add_u64 v[112:113], v[112:113], 0, v[144:145]
	global_store_dwordx4 v[112:113], v[104:107], off nt
	v_pk_mul_f32 v[80:81], v[84:85], v[80:81]
	v_mul_f32_e32 v84, 0xbfb8aa3b, v78
	v_cvt_pk_bf16_f32 v90, v80, v81
	v_pk_mul_f32 v[80:81], v[86:87], v[92:93]
	v_mul_f32_e32 v85, 0xbfb8aa3b, v79
	v_pk_mul_f32 v[80:81], v[80:81], v[82:83]
	v_mul_f32_e32 v82, 0xbfb8aa3b, v76
	v_mul_f32_e32 v83, 0xbfb8aa3b, v77
	v_exp_f32_e32 v82, v82
	v_exp_f32_e32 v83, v83
	v_exp_f32_e32 v84, v84
	v_exp_f32_e32 v85, v85
	v_add_f32_e32 v82, 1.0, v82
	v_add_f32_e32 v83, 1.0, v83
	v_rcp_f32_e32 v82, v82
; __device__ __forceinline__ unsigned pk2(float lo, float hi) { const f32x2c v = {lo, hi}; const bf16x2c b = __builtin_convertvector(v, bf16x2c); return __builtin_bit_cast(unsigned, b); }
; __device__ __forceinline__ float silu_f(float x) { return x * fast_sigmoid(x); }
;     __device__ __forceinline__ void operator()(const f32x4 (&acc)[2][2][4][2], const pg8::Unit& u, int wr, int wc, int fr, int fq) const {
;     ...
; #pragma unroll
;         for (int ai = 0; ai < 2; ++ai)
; #pragma unroll
;             for (int m = 0; m < 4; ++m) {
;                 bf16_t* rowp = O + (size_t)(row0 + ai * 128 + m * 16) * ldc + col0;
;                 const f32x4 a0 = acc[ai][0][m][0], a1 = acc[ai][0][m][1], b0 = acc[ai][1][m][0], b1 = acc[ai][1][m][1];
;                 u32x4 w;
;                 w.x = pk2(silu_f(a0[0]) * b0[0], silu_f(a0[1]) * b0[1]); w.y = pk2(silu_f(a0[2]) * b0[2], silu_f(a0[3]) * b0[3]);
;                 w.z = pk2(silu_f(a1[0]) * b1[0], silu_f(a1[1]) * b1[1]); w.w = pk2(silu_f(a1[2]) * b1[2], silu_f(a1[3]) * b1[3]);
;                 *(u32x4*)rowp = w;
;             }
	v_rcp_f32_e32 v83, v83
	v_add_f32_e32 v84, 1.0, v84
	v_add_f32_e32 v85, 1.0, v85
	v_rcp_f32_e32 v84, v84
	v_rcp_f32_e32 v85, v85
	v_pk_mul_f32 v[76:77], v[76:77], v[82:83]
	v_or_b32_e32 v96, 32, v154
	v_pk_mul_f32 v[72:73], v[76:77], v[72:73]
	v_pk_mul_f32 v[76:77], v[78:79], v[84:85]
	v_cvt_pk_bf16_f32 v72, v72, v73
	v_mul_f32_e32 v73, 0xbfb8aa3b, v68
	v_pk_mul_f32 v[74:75], v[76:77], v[74:75]
	v_exp_f32_e32 v76, v73
	v_mul_f32_e32 v73, 0xbfb8aa3b, v69
	v_exp_f32_e32 v77, v73
	v_cvt_pk_bf16_f32 v73, v74, v75
	v_add_f32_e32 v74, 1.0, v76
	v_mul_f32_e32 v76, 0xbfb8aa3b, v70
	v_add_f32_e32 v75, 1.0, v77
	v_mul_f32_e32 v77, 0xbfb8aa3b, v71
	v_exp_f32_e32 v76, v76
	v_exp_f32_e32 v77, v77
	v_rcp_f32_e32 v74, v74
	v_rcp_f32_e32 v75, v75
	v_add_f32_e32 v76, 1.0, v76
	v_add_f32_e32 v77, 1.0, v77
	v_rcp_f32_e32 v76, v76
	v_rcp_f32_e32 v77, v77
	v_pk_mul_f32 v[68:69], v[68:69], v[74:75]
	v_cvt_pk_bf16_f32 v91, v80, v81
	v_mad_i64_i32 v[96:97], s[30:31], v96, s70, v[146:147]
	v_lshl_add_u64 v[96:97], v[96:97], 0, v[144:145]
	global_store_dwordx4 v[96:97], v[88:91], off nt
	v_pk_mul_f32 v[64:65], v[68:69], v[64:65]
	v_mul_f32_e32 v68, 0xbfb8aa3b, v62
	v_cvt_pk_bf16_f32 v74, v64, v65
	v_pk_mul_f32 v[64:65], v[70:71], v[76:77]
	v_mul_f32_e32 v69, 0xbfb8aa3b, v63
	v_pk_mul_f32 v[64:65], v[64:65], v[66:67]
	v_mul_f32_e32 v66, 0xbfb8aa3b, v60
	v_mul_f32_e32 v67, 0xbfb8aa3b, v61
	v_exp_f32_e32 v66, v66
	v_exp_f32_e32 v67, v67
	v_exp_f32_e32 v68, v68
	v_exp_f32_e32 v69, v69
	v_add_f32_e32 v66, 1.0, v66
	v_add_f32_e32 v67, 1.0, v67
	v_rcp_f32_e32 v66, v66
	v_rcp_f32_e32 v67, v67
	v_add_f32_e32 v68, 1.0, v68
	v_add_f32_e32 v69, 1.0, v69
	v_rcp_f32_e32 v68, v68
	v_rcp_f32_e32 v69, v69
	v_pk_mul_f32 v[60:61], v[60:61], v[66:67]
	v_or_b32_e32 v80, 48, v154
	v_pk_mul_f32 v[56:57], v[60:61], v[56:57]
	v_pk_mul_f32 v[60:61], v[62:63], v[68:69]
	v_cvt_pk_bf16_f32 v56, v56, v57
	v_mul_f32_e32 v57, 0xbfb8aa3b, v52
	v_pk_mul_f32 v[58:59], v[60:61], v[58:59]
	v_exp_f32_e32 v60, v57
	v_mul_f32_e32 v57, 0xbfb8aa3b, v53
	v_exp_f32_e32 v61, v57
	v_cvt_pk_bf16_f32 v57, v58, v59
	v_add_f32_e32 v58, 1.0, v60
	v_mul_f32_e32 v60, 0xbfb8aa3b, v54
	v_add_f32_e32 v59, 1.0, v61
	v_mul_f32_e32 v61, 0xbfb8aa3b, v55
	v_exp_f32_e32 v60, v60
	v_exp_f32_e32 v61, v61
	v_rcp_f32_e32 v58, v58
	v_rcp_f32_e32 v59, v59
	v_add_f32_e32 v60, 1.0, v60
	v_add_f32_e32 v61, 1.0, v61
	v_rcp_f32_e32 v60, v60
	v_rcp_f32_e32 v61, v61
	v_pk_mul_f32 v[52:53], v[52:53], v[58:59]
	v_cvt_pk_bf16_f32 v75, v64, v65
	v_mad_i64_i32 v[80:81], s[30:31], v80, s70, v[146:147]
	v_lshl_add_u64 v[80:81], v[80:81], 0, v[144:145]
	global_store_dwordx4 v[80:81], v[72:75], off nt
	v_pk_mul_f32 v[48:49], v[52:53], v[48:49]
	v_mul_f32_e32 v52, 0xbfb8aa3b, v46
	v_cvt_pk_bf16_f32 v58, v48, v49
	v_pk_mul_f32 v[48:49], v[54:55], v[60:61]
	v_mul_f32_e32 v53, 0xbfb8aa3b, v47
	v_pk_mul_f32 v[48:49], v[48:49], v[50:51]
	v_mul_f32_e32 v50, 0xbfb8aa3b, v44
	v_mul_f32_e32 v51, 0xbfb8aa3b, v45
	v_exp_f32_e32 v50, v50
	v_exp_f32_e32 v51, v51
	v_exp_f32_e32 v52, v52
	v_exp_f32_e32 v53, v53
	v_add_f32_e32 v50, 1.0, v50
	v_add_f32_e32 v51, 1.0, v51
	v_rcp_f32_e32 v50, v50
	v_rcp_f32_e32 v51, v51
	v_add_f32_e32 v52, 1.0, v52
	v_add_f32_e32 v53, 1.0, v53
	v_rcp_f32_e32 v52, v52
	v_rcp_f32_e32 v53, v53
	v_pk_mul_f32 v[44:45], v[44:45], v[50:51]
	v_add_u32_e32 v64, 0x80, v154
	v_pk_mul_f32 v[40:41], v[44:45], v[40:41]
	v_pk_mul_f32 v[44:45], v[46:47], v[52:53]
	v_cvt_pk_bf16_f32 v40, v40, v41
	v_mul_f32_e32 v41, 0xbfb8aa3b, v36
	v_pk_mul_f32 v[42:43], v[44:45], v[42:43]
	v_exp_f32_e32 v44, v41
	v_mul_f32_e32 v41, 0xbfb8aa3b, v37
	v_exp_f32_e32 v45, v41
	v_cvt_pk_bf16_f32 v41, v42, v43
	v_add_f32_e32 v42, 1.0, v44
	v_mul_f32_e32 v44, 0xbfb8aa3b, v38
	v_add_f32_e32 v43, 1.0, v45
	v_mul_f32_e32 v45, 0xbfb8aa3b, v39
	v_exp_f32_e32 v44, v44
	v_exp_f32_e32 v45, v45
	v_rcp_f32_e32 v42, v42
	v_rcp_f32_e32 v43, v43
	v_add_f32_e32 v44, 1.0, v44
	v_add_f32_e32 v45, 1.0, v45
; #define PG8_BAR __builtin_amdgcn_s_barrier()
; __device__ __forceinline__ unsigned pk2(float lo, float hi) { const f32x2c v = {lo, hi}; const bf16x2c b = __builtin_convertvector(v, bf16x2c); return __builtin_bit_cast(unsigned, b); }
; __device__ __forceinline__ float silu_f(float x) { return x * fast_sigmoid(x); }
; template <class Epi, class Sched, bool ALIGN_EPI = false, bool SP2 = false>
; __device__ __forceinline__ void gemm_phase(PG8_LAS unsigned char* lds, const Gemm g, const Sched& S, const Epi& E, const int wid) {
;     ...
;         if (!has_next) break;
; #pragma unroll
;         for (int a = 0; a < 2; ++a)
; #pragma unroll
;             for (int b = 0; b < 2; ++b)
; #pragma unroll
;                 for (int m = 0; m < 4; ++m)
; #pragma unroll
;                     for (int n = 0; n < 2; ++n) acc[a][b][m][n] = (f32x4){0.f, 0.f, 0.f, 0.f};
;         cur = nxt; cA = nA; cB = nB; ++ui;
;         if constexpr (ALIGN_EPI) { if (wr == 1) PG8_BAR; }
;     __device__ __forceinline__ void operator()(const f32x4 (&acc)[2][2][4][2], const pg8::Unit& u, int wr, int wc, int fr, int fq) const {
;     ...
; #pragma unroll
;         for (int ai = 0; ai < 2; ++ai)
; #pragma unroll
;             for (int m = 0; m < 4; ++m) {
;                 bf16_t* rowp = O + (size_t)(row0 + ai * 128 + m * 16) * ldc + col0;
;                 const f32x4 a0 = acc[ai][0][m][0], a1 = acc[ai][0][m][1], b0 = acc[ai][1][m][0], b1 = acc[ai][1][m][1];
;                 u32x4 w;
;                 w.x = pk2(silu_f(a0[0]) * b0[0], silu_f(a0[1]) * b0[1]); w.y = pk2(silu_f(a0[2]) * b0[2], silu_f(a0[3]) * b0[3]);
;                 w.z = pk2(silu_f(a1[0]) * b1[0], silu_f(a1[1]) * b1[1]); w.w = pk2(silu_f(a1[2]) * b1[2], silu_f(a1[3]) * b1[3]);
;                 *(u32x4*)rowp = w;
;             }
	v_rcp_f32_e32 v44, v44
	v_rcp_f32_e32 v45, v45
	v_pk_mul_f32 v[36:37], v[36:37], v[42:43]
	v_cvt_pk_bf16_f32 v59, v48, v49
	v_mad_i64_i32 v[64:65], s[30:31], v64, s70, v[146:147]
	v_lshl_add_u64 v[64:65], v[64:65], 0, v[144:145]
	global_store_dwordx4 v[64:65], v[56:59], off nt
	v_pk_mul_f32 v[32:33], v[36:37], v[32:33]
	v_mul_f32_e32 v36, 0xbfb8aa3b, v30
	v_cvt_pk_bf16_f32 v42, v32, v33
	v_pk_mul_f32 v[32:33], v[38:39], v[44:45]
	v_mul_f32_e32 v37, 0xbfb8aa3b, v31
	v_pk_mul_f32 v[32:33], v[32:33], v[34:35]
	v_mul_f32_e32 v34, 0xbfb8aa3b, v28
	v_mul_f32_e32 v35, 0xbfb8aa3b, v29
	v_exp_f32_e32 v34, v34
	v_exp_f32_e32 v35, v35
	v_exp_f32_e32 v36, v36
	v_exp_f32_e32 v37, v37
	v_add_f32_e32 v34, 1.0, v34
	v_add_f32_e32 v35, 1.0, v35
	v_rcp_f32_e32 v34, v34
	v_rcp_f32_e32 v35, v35
	v_add_f32_e32 v36, 1.0, v36
	v_add_f32_e32 v37, 1.0, v37
	v_rcp_f32_e32 v36, v36
	v_rcp_f32_e32 v37, v37
	v_pk_mul_f32 v[28:29], v[28:29], v[34:35]
	v_add_u32_e32 v48, 0x90, v154
	v_pk_mul_f32 v[24:25], v[28:29], v[24:25]
	v_pk_mul_f32 v[28:29], v[30:31], v[36:37]
	v_cvt_pk_bf16_f32 v24, v24, v25
	v_mul_f32_e32 v25, 0xbfb8aa3b, v20
	v_pk_mul_f32 v[26:27], v[28:29], v[26:27]
	v_exp_f32_e32 v28, v25
	v_mul_f32_e32 v25, 0xbfb8aa3b, v21
	v_exp_f32_e32 v29, v25
	v_cvt_pk_bf16_f32 v25, v26, v27
	v_add_f32_e32 v26, 1.0, v28
	v_mul_f32_e32 v28, 0xbfb8aa3b, v22
	v_add_f32_e32 v27, 1.0, v29
	v_mul_f32_e32 v29, 0xbfb8aa3b, v23
	v_exp_f32_e32 v28, v28
	v_exp_f32_e32 v29, v29
	v_rcp_f32_e32 v26, v26
	v_rcp_f32_e32 v27, v27
	v_add_f32_e32 v28, 1.0, v28
	v_add_f32_e32 v29, 1.0, v29
	v_rcp_f32_e32 v28, v28
	v_rcp_f32_e32 v29, v29
	v_pk_mul_f32 v[20:21], v[20:21], v[26:27]
	v_cvt_pk_bf16_f32 v43, v32, v33
	v_mad_i64_i32 v[48:49], s[30:31], v48, s70, v[146:147]
	v_lshl_add_u64 v[48:49], v[48:49], 0, v[144:145]
	global_store_dwordx4 v[48:49], v[40:43], off nt
	v_pk_mul_f32 v[16:17], v[20:21], v[16:17]
	v_mul_f32_e32 v20, 0xbfb8aa3b, v14
	v_cvt_pk_bf16_f32 v26, v16, v17
	v_pk_mul_f32 v[16:17], v[22:23], v[28:29]
	v_mul_f32_e32 v21, 0xbfb8aa3b, v15
	v_pk_mul_f32 v[16:17], v[16:17], v[18:19]
	v_mul_f32_e32 v18, 0xbfb8aa3b, v12
	v_mul_f32_e32 v19, 0xbfb8aa3b, v13
	v_exp_f32_e32 v18, v18
	v_exp_f32_e32 v19, v19
	v_exp_f32_e32 v20, v20
	v_exp_f32_e32 v21, v21
	v_add_f32_e32 v18, 1.0, v18
	v_add_f32_e32 v19, 1.0, v19
	v_rcp_f32_e32 v18, v18
	v_rcp_f32_e32 v19, v19
	v_add_f32_e32 v20, 1.0, v20
	v_add_f32_e32 v21, 1.0, v21
	v_rcp_f32_e32 v20, v20
	v_rcp_f32_e32 v21, v21
	v_pk_mul_f32 v[12:13], v[12:13], v[18:19]
	v_add_u32_e32 v32, 0xa0, v154
	v_pk_mul_f32 v[8:9], v[12:13], v[8:9]
	v_pk_mul_f32 v[12:13], v[14:15], v[20:21]
	v_cvt_pk_bf16_f32 v8, v8, v9
	v_mul_f32_e32 v9, 0xbfb8aa3b, v4
	v_pk_mul_f32 v[10:11], v[12:13], v[10:11]
	v_exp_f32_e32 v12, v9
	v_mul_f32_e32 v9, 0xbfb8aa3b, v5
	v_exp_f32_e32 v13, v9
	v_cvt_pk_bf16_f32 v9, v10, v11
	v_add_f32_e32 v10, 1.0, v12
	v_mul_f32_e32 v12, 0xbfb8aa3b, v6
	v_add_f32_e32 v11, 1.0, v13
	v_mul_f32_e32 v13, 0xbfb8aa3b, v7
	v_exp_f32_e32 v12, v12
	v_exp_f32_e32 v13, v13
	v_rcp_f32_e32 v10, v10
	v_rcp_f32_e32 v11, v11
	v_add_f32_e32 v12, 1.0, v12
	v_add_f32_e32 v13, 1.0, v13
	v_rcp_f32_e32 v12, v12
	v_rcp_f32_e32 v13, v13
	v_pk_mul_f32 v[4:5], v[4:5], v[10:11]
	v_cvt_pk_bf16_f32 v27, v16, v17
	v_mad_i64_i32 v[32:33], s[30:31], v32, s70, v[146:147]
	v_lshl_add_u64 v[32:33], v[32:33], 0, v[144:145]
	global_store_dwordx4 v[32:33], v[24:27], off nt
	v_pk_mul_f32 v[0:1], v[4:5], v[0:1]
	v_add_u32_e32 v16, 0xb0, v154
	v_cvt_pk_bf16_f32 v10, v0, v1
	v_pk_mul_f32 v[0:1], v[6:7], v[12:13]
	v_pk_mul_f32 v[0:1], v[0:1], v[2:3]
	v_cvt_pk_bf16_f32 v11, v0, v1
	v_mad_i64_i32 v[16:17], s[30:31], v16, s70, v[146:147]
	v_lshl_add_u64 v[16:17], v[16:17], 0, v[144:145]
	global_store_dwordx4 v[16:17], v[8:11], off nt
	s_andn2_b64 vcc, exec, s[4:5]
	s_mov_b64 s[4:5], -1
	s_cbranch_vccnz .LBB0_146
	s_andn2_b64 vcc, exec, s[6:7]
	s_cbranch_vccnz .LBB0_145
	s_barrier
	s_branch .LBB0_145

; __device__ __forceinline__ unsigned pk2(float lo, float hi) { const f32x2c v = {lo, hi}; const bf16x2c b = __builtin_convertvector(v, bf16x2c); return __builtin_bit_cast(unsigned, b); }
; __device__ __forceinline__ float fast_sigmoid(float x) { return __builtin_amdgcn_rcpf(1.f + __expf(-x)); }
; __device__ __forceinline__ float silu_f(float x) { return x * fast_sigmoid(x); }
;     __device__ __forceinline__ void operator()(const f32x4 (&acc)[2][2][4][2], const pg8::Unit& u, int wr, int wc, int fr, int fq) const {
;         const int row0 = u.pm * 256 + wr * 64 + fr, col0 = u.pn * 128 + wc * 32 + 8 * fq;
; #pragma unroll
;         for (int ai = 0; ai < 2; ++ai)
; #pragma unroll
;             for (int m = 0; m < 4; ++m) {
;                 bf16_t* rowp = O + (size_t)(row0 + ai * 128 + m * 16) * ldc + col0;
;                 const f32x4 a0 = acc[ai][0][m][0], a1 = acc[ai][0][m][1], b0 = acc[ai][1][m][0], b1 = acc[ai][1][m][1];
;                 u32x4 w;
;                 w.x = pk2(silu_f(a0[0]) * b0[0], silu_f(a0[1]) * b0[1]); w.y = pk2(silu_f(a0[2]) * b0[2], silu_f(a0[3]) * b0[3]);
;                 w.z = pk2(silu_f(a1[0]) * b1[0], silu_f(a1[1]) * b1[1]); w.w = pk2(silu_f(a1[2]) * b1[2], silu_f(a1[3]) * b1[3]);
;                 *(u32x4*)rowp = w;
;             }
.LBB0_1314:
	v_mul_f32_e32 v155, 0xbfb8aa3b, v124
	v_exp_f32_e32 v155, v155
	v_mul_f32_e32 v158, 0xbfb8aa3b, v125
	v_exp_f32_e32 v159, v158
	v_lshl_add_u32 v154, s20, 8, v148
	v_add_f32_e32 v155, 1.0, v155
	v_rcp_f32_e32 v158, v155
	v_add_f32_e32 v155, 1.0, v159
	v_mul_f32_e32 v159, 0xbfb8aa3b, v126
	v_exp_f32_e32 v160, v159
	v_mul_f32_e32 v159, 0xbfb8aa3b, v127
	v_exp_f32_e32 v161, v159
	v_rcp_f32_e32 v159, v155
	v_add_f32_e32 v155, 1.0, v160
	v_rcp_f32_e32 v160, v155
	v_add_f32_e32 v155, 1.0, v161
	v_rcp_f32_e32 v161, v155
	v_pk_mul_f32 v[124:125], v[124:125], v[158:159]
	v_lshl_add_u32 v144, s45, 7, v150
	v_pk_mul_f32 v[120:121], v[124:125], v[120:121]
	v_pk_mul_f32 v[124:125], v[126:127], v[160:161]
	v_cvt_pk_bf16_f32 v120, v120, v121
	v_mul_f32_e32 v121, 0xbfb8aa3b, v116
	v_pk_mul_f32 v[122:123], v[124:125], v[122:123]
	v_exp_f32_e32 v124, v121
	v_mul_f32_e32 v121, 0xbfb8aa3b, v117
	v_exp_f32_e32 v125, v121
	v_cvt_pk_bf16_f32 v121, v122, v123
	v_add_f32_e32 v122, 1.0, v124
	v_mul_f32_e32 v124, 0xbfb8aa3b, v118
	v_add_f32_e32 v123, 1.0, v125
	v_mul_f32_e32 v125, 0xbfb8aa3b, v119
	v_exp_f32_e32 v124, v124
	v_exp_f32_e32 v125, v125
	v_rcp_f32_e32 v122, v122
	v_rcp_f32_e32 v123, v123
	v_add_f32_e32 v124, 1.0, v124
	v_add_f32_e32 v125, 1.0, v125
	v_rcp_f32_e32 v124, v124
	v_rcp_f32_e32 v125, v125
	v_pk_mul_f32 v[116:117], v[116:117], v[122:123]
	v_ashrrev_i32_e32 v145, 31, v144
	v_pk_mul_f32 v[112:113], v[116:117], v[112:113]
	v_mul_f32_e32 v116, 0xbfb8aa3b, v110
	v_cvt_pk_bf16_f32 v122, v112, v113
	v_pk_mul_f32 v[112:113], v[118:119], v[124:125]
	v_mul_f32_e32 v117, 0xbfb8aa3b, v111
	v_pk_mul_f32 v[112:113], v[112:113], v[114:115]
	v_mul_f32_e32 v114, 0xbfb8aa3b, v108
	v_mul_f32_e32 v115, 0xbfb8aa3b, v109
	v_exp_f32_e32 v114, v114
	v_exp_f32_e32 v115, v115
	v_exp_f32_e32 v116, v116
	v_exp_f32_e32 v117, v117
	v_add_f32_e32 v114, 1.0, v114
	v_add_f32_e32 v115, 1.0, v115
	v_rcp_f32_e32 v114, v114
	v_rcp_f32_e32 v115, v115
	v_add_f32_e32 v116, 1.0, v116
	v_add_f32_e32 v117, 1.0, v117
	v_rcp_f32_e32 v116, v116
	v_rcp_f32_e32 v117, v117
	v_pk_mul_f32 v[108:109], v[108:109], v[114:115]
	s_cselect_b32 s98, 1, 0
	s_lshr_b32 s99, s20, 1
	s_and_b32 s100, s99, 7
	s_lshl_b32 s100, s100, 1
	s_bfe_u32 s101, s99, 0x10003
	s_or_b32 s100, s100, s101
	s_and_b32 s101, s99, 0x30
	s_or_b32 s100, s100, s101
	s_mul_i32 s100, s100, 0x300000
	s_mul_i32 s99, s99, 0x2c0000
	s_add_u32 s100, s100, 0xd000000
	s_sub_u32 s100, s100, s99
	s_add_u32 s100, s96, s100
	s_addc_u32 s101, s97, 0
	s_cmp_lg_u32 s98, 0
	v_mov_b64_e32 v[146:147], s[100:101]
	v_pk_mul_f32 v[104:105], v[108:109], v[104:105]
	v_pk_mul_f32 v[108:109], v[110:111], v[116:117]
	v_cvt_pk_bf16_f32 v104, v104, v105
	v_mul_f32_e32 v105, 0xbfb8aa3b, v100
	v_pk_mul_f32 v[106:107], v[108:109], v[106:107]
	v_exp_f32_e32 v108, v105
	v_mul_f32_e32 v105, 0xbfb8aa3b, v101
	v_exp_f32_e32 v109, v105
	v_cvt_pk_bf16_f32 v105, v106, v107
	v_add_f32_e32 v106, 1.0, v108
	v_mul_f32_e32 v108, 0xbfb8aa3b, v102
	v_add_f32_e32 v107, 1.0, v109
	v_mul_f32_e32 v109, 0xbfb8aa3b, v103
	v_exp_f32_e32 v108, v108
	v_exp_f32_e32 v109, v109
	v_rcp_f32_e32 v106, v106
	v_rcp_f32_e32 v107, v107
	v_add_f32_e32 v108, 1.0, v108
	v_add_f32_e32 v109, 1.0, v109
	v_rcp_f32_e32 v108, v108
	v_rcp_f32_e32 v109, v109
	v_pk_mul_f32 v[100:101], v[100:101], v[106:107]
	v_cvt_pk_bf16_f32 v123, v112, v113
	v_lshlrev_b64 v[144:145], 1, v[144:145]
	v_mad_i64_i32 v[156:157], s[22:23], v154, s44, v[146:147]
	v_lshl_add_u64 v[156:157], v[156:157], 0, v[144:145]
	global_store_dwordx4 v[156:157], v[120:123], off nt
	v_pk_mul_f32 v[96:97], v[100:101], v[96:97]
	v_mul_f32_e32 v100, 0xbfb8aa3b, v94
	v_cvt_pk_bf16_f32 v106, v96, v97
	v_pk_mul_f32 v[96:97], v[102:103], v[108:109]
	v_mul_f32_e32 v101, 0xbfb8aa3b, v95
	v_pk_mul_f32 v[96:97], v[96:97], v[98:99]
	v_mul_f32_e32 v98, 0xbfb8aa3b, v92
	v_mul_f32_e32 v99, 0xbfb8aa3b, v93
	v_exp_f32_e32 v98, v98
	v_exp_f32_e32 v99, v99
	v_exp_f32_e32 v100, v100
	v_exp_f32_e32 v101, v101
	v_add_f32_e32 v98, 1.0, v98
	v_add_f32_e32 v99, 1.0, v99
	v_rcp_f32_e32 v98, v98
	v_rcp_f32_e32 v99, v99
	v_add_f32_e32 v100, 1.0, v100
	v_add_f32_e32 v101, 1.0, v101
	v_rcp_f32_e32 v100, v100
	v_rcp_f32_e32 v101, v101
	v_pk_mul_f32 v[92:93], v[92:93], v[98:99]
	v_or_b32_e32 v112, 16, v154
	v_pk_mul_f32 v[88:89], v[92:93], v[88:89]
	v_pk_mul_f32 v[92:93], v[94:95], v[100:101]
	v_cvt_pk_bf16_f32 v88, v88, v89
	v_mul_f32_e32 v89, 0xbfb8aa3b, v84
	v_pk_mul_f32 v[90:91], v[92:93], v[90:91]
	v_exp_f32_e32 v92, v89
	v_mul_f32_e32 v89, 0xbfb8aa3b, v85
	v_exp_f32_e32 v93, v89
	v_cvt_pk_bf16_f32 v89, v90, v91
	v_add_f32_e32 v90, 1.0, v92
	v_mul_f32_e32 v92, 0xbfb8aa3b, v86
	v_add_f32_e32 v91, 1.0, v93
	v_mul_f32_e32 v93, 0xbfb8aa3b, v87
	v_exp_f32_e32 v92, v92
	v_exp_f32_e32 v93, v93
	v_rcp_f32_e32 v90, v90
	v_rcp_f32_e32 v91, v91
	v_add_f32_e32 v92, 1.0, v92
	v_add_f32_e32 v93, 1.0, v93
	v_rcp_f32_e32 v92, v92
	v_rcp_f32_e32 v93, v93
	v_pk_mul_f32 v[84:85], v[84:85], v[90:91]
	v_cvt_pk_bf16_f32 v107, v96, v97
	v_mad_i64_i32 v[112:113], s[22:23], v112, s44, v[146:147]
	v_lshl_add_u64 v[112:113], v[112:113], 0, v[144:145]
	global_store_dwordx4 v[112:113], v[104:107], off nt
	v_pk_mul_f32 v[80:81], v[84:85], v[80:81]
	v_mul_f32_e32 v84, 0xbfb8aa3b, v78
	v_cvt_pk_bf16_f32 v90, v80, v81
	v_pk_mul_f32 v[80:81], v[86:87], v[92:93]
	v_mul_f32_e32 v85, 0xbfb8aa3b, v79
	v_pk_mul_f32 v[80:81], v[80:81], v[82:83]
	v_mul_f32_e32 v82, 0xbfb8aa3b, v76
	v_mul_f32_e32 v83, 0xbfb8aa3b, v77
	v_exp_f32_e32 v82, v82
	v_exp_f32_e32 v83, v83
	v_exp_f32_e32 v84, v84
	v_exp_f32_e32 v85, v85
	v_add_f32_e32 v82, 1.0, v82
	v_add_f32_e32 v83, 1.0, v83
	v_rcp_f32_e32 v82, v82
; __device__ __forceinline__ unsigned pk2(float lo, float hi) { const f32x2c v = {lo, hi}; const bf16x2c b = __builtin_convertvector(v, bf16x2c); return __builtin_bit_cast(unsigned, b); }
; __device__ __forceinline__ float silu_f(float x) { return x * fast_sigmoid(x); }
;     __device__ __forceinline__ void operator()(const f32x4 (&acc)[2][2][4][2], const pg8::Unit& u, int wr, int wc, int fr, int fq) const {
;     ...
; #pragma unroll
;         for (int ai = 0; ai < 2; ++ai)
; #pragma unroll
;             for (int m = 0; m < 4; ++m) {
;                 bf16_t* rowp = O + (size_t)(row0 + ai * 128 + m * 16) * ldc + col0;
;                 const f32x4 a0 = acc[ai][0][m][0], a1 = acc[ai][0][m][1], b0 = acc[ai][1][m][0], b1 = acc[ai][1][m][1];
;                 u32x4 w;
;                 w.x = pk2(silu_f(a0[0]) * b0[0], silu_f(a0[1]) * b0[1]); w.y = pk2(silu_f(a0[2]) * b0[2], silu_f(a0[3]) * b0[3]);
;                 w.z = pk2(silu_f(a1[0]) * b1[0], silu_f(a1[1]) * b1[1]); w.w = pk2(silu_f(a1[2]) * b1[2], silu_f(a1[3]) * b1[3]);
;                 *(u32x4*)rowp = w;
;             }
	v_rcp_f32_e32 v83, v83
	v_add_f32_e32 v84, 1.0, v84
	v_add_f32_e32 v85, 1.0, v85
	v_rcp_f32_e32 v84, v84
	v_rcp_f32_e32 v85, v85
	v_pk_mul_f32 v[76:77], v[76:77], v[82:83]
	v_or_b32_e32 v96, 32, v154
	v_pk_mul_f32 v[72:73], v[76:77], v[72:73]
	v_pk_mul_f32 v[76:77], v[78:79], v[84:85]
	v_cvt_pk_bf16_f32 v72, v72, v73
	v_mul_f32_e32 v73, 0xbfb8aa3b, v68
	v_pk_mul_f32 v[74:75], v[76:77], v[74:75]
	v_exp_f32_e32 v76, v73
	v_mul_f32_e32 v73, 0xbfb8aa3b, v69
	v_exp_f32_e32 v77, v73
	v_cvt_pk_bf16_f32 v73, v74, v75
	v_add_f32_e32 v74, 1.0, v76
	v_mul_f32_e32 v76, 0xbfb8aa3b, v70
	v_add_f32_e32 v75, 1.0, v77
	v_mul_f32_e32 v77, 0xbfb8aa3b, v71
	v_exp_f32_e32 v76, v76
	v_exp_f32_e32 v77, v77
	v_rcp_f32_e32 v74, v74
	v_rcp_f32_e32 v75, v75
	v_add_f32_e32 v76, 1.0, v76
	v_add_f32_e32 v77, 1.0, v77
	v_rcp_f32_e32 v76, v76
	v_rcp_f32_e32 v77, v77
	v_pk_mul_f32 v[68:69], v[68:69], v[74:75]
	v_cvt_pk_bf16_f32 v91, v80, v81
	v_mad_i64_i32 v[96:97], s[22:23], v96, s44, v[146:147]
	v_lshl_add_u64 v[96:97], v[96:97], 0, v[144:145]
	global_store_dwordx4 v[96:97], v[88:91], off nt
	v_pk_mul_f32 v[64:65], v[68:69], v[64:65]
	v_mul_f32_e32 v68, 0xbfb8aa3b, v62
	v_cvt_pk_bf16_f32 v74, v64, v65
	v_pk_mul_f32 v[64:65], v[70:71], v[76:77]
	v_mul_f32_e32 v69, 0xbfb8aa3b, v63
	v_pk_mul_f32 v[64:65], v[64:65], v[66:67]
	v_mul_f32_e32 v66, 0xbfb8aa3b, v60
	v_mul_f32_e32 v67, 0xbfb8aa3b, v61
	v_exp_f32_e32 v66, v66
	v_exp_f32_e32 v67, v67
	v_exp_f32_e32 v68, v68
	v_exp_f32_e32 v69, v69
	v_add_f32_e32 v66, 1.0, v66
	v_add_f32_e32 v67, 1.0, v67
	v_rcp_f32_e32 v66, v66
	v_rcp_f32_e32 v67, v67
	v_add_f32_e32 v68, 1.0, v68
	v_add_f32_e32 v69, 1.0, v69
	v_rcp_f32_e32 v68, v68
	v_rcp_f32_e32 v69, v69
	v_pk_mul_f32 v[60:61], v[60:61], v[66:67]
	v_or_b32_e32 v80, 48, v154
	v_pk_mul_f32 v[56:57], v[60:61], v[56:57]
	v_pk_mul_f32 v[60:61], v[62:63], v[68:69]
	v_cvt_pk_bf16_f32 v56, v56, v57
	v_mul_f32_e32 v57, 0xbfb8aa3b, v52
	v_pk_mul_f32 v[58:59], v[60:61], v[58:59]
	v_exp_f32_e32 v60, v57
	v_mul_f32_e32 v57, 0xbfb8aa3b, v53
	v_exp_f32_e32 v61, v57
	v_cvt_pk_bf16_f32 v57, v58, v59
	v_add_f32_e32 v58, 1.0, v60
	v_mul_f32_e32 v60, 0xbfb8aa3b, v54
	v_add_f32_e32 v59, 1.0, v61
	v_mul_f32_e32 v61, 0xbfb8aa3b, v55
	v_exp_f32_e32 v60, v60
	v_exp_f32_e32 v61, v61
	v_rcp_f32_e32 v58, v58
	v_rcp_f32_e32 v59, v59
	v_add_f32_e32 v60, 1.0, v60
	v_add_f32_e32 v61, 1.0, v61
	v_rcp_f32_e32 v60, v60
	v_rcp_f32_e32 v61, v61
	v_pk_mul_f32 v[52:53], v[52:53], v[58:59]
	v_cvt_pk_bf16_f32 v75, v64, v65
	v_mad_i64_i32 v[80:81], s[22:23], v80, s44, v[146:147]
	v_lshl_add_u64 v[80:81], v[80:81], 0, v[144:145]
	global_store_dwordx4 v[80:81], v[72:75], off nt
	v_pk_mul_f32 v[48:49], v[52:53], v[48:49]
	v_mul_f32_e32 v52, 0xbfb8aa3b, v46
	v_cvt_pk_bf16_f32 v58, v48, v49
	v_pk_mul_f32 v[48:49], v[54:55], v[60:61]
	v_mul_f32_e32 v53, 0xbfb8aa3b, v47
	v_pk_mul_f32 v[48:49], v[48:49], v[50:51]
	v_mul_f32_e32 v50, 0xbfb8aa3b, v44
	v_mul_f32_e32 v51, 0xbfb8aa3b, v45
	v_exp_f32_e32 v50, v50
	v_exp_f32_e32 v51, v51
	v_exp_f32_e32 v52, v52
	v_exp_f32_e32 v53, v53
	v_add_f32_e32 v50, 1.0, v50
	v_add_f32_e32 v51, 1.0, v51
	v_rcp_f32_e32 v50, v50
	v_rcp_f32_e32 v51, v51
	v_add_f32_e32 v52, 1.0, v52
	v_add_f32_e32 v53, 1.0, v53
	v_rcp_f32_e32 v52, v52
	v_rcp_f32_e32 v53, v53
	v_pk_mul_f32 v[44:45], v[44:45], v[50:51]
	v_add_u32_e32 v64, 0x80, v154
	v_pk_mul_f32 v[40:41], v[44:45], v[40:41]
	v_pk_mul_f32 v[44:45], v[46:47], v[52:53]
	v_cvt_pk_bf16_f32 v40, v40, v41
	v_mul_f32_e32 v41, 0xbfb8aa3b, v36
	v_pk_mul_f32 v[42:43], v[44:45], v[42:43]
	v_exp_f32_e32 v44, v41
	v_mul_f32_e32 v41, 0xbfb8aa3b, v37
	v_exp_f32_e32 v45, v41
	v_cvt_pk_bf16_f32 v41, v42, v43
	v_add_f32_e32 v42, 1.0, v44
	v_mul_f32_e32 v44, 0xbfb8aa3b, v38
	v_add_f32_e32 v43, 1.0, v45
	v_mul_f32_e32 v45, 0xbfb8aa3b, v39
	v_exp_f32_e32 v44, v44
	v_exp_f32_e32 v45, v45
	v_rcp_f32_e32 v42, v42
	v_rcp_f32_e32 v43, v43
	v_add_f32_e32 v44, 1.0, v44
	v_add_f32_e32 v45, 1.0, v45
; #define PG8_BAR __builtin_amdgcn_s_barrier()
; __device__ __forceinline__ unsigned pk2(float lo, float hi) { const f32x2c v = {lo, hi}; const bf16x2c b = __builtin_convertvector(v, bf16x2c); return __builtin_bit_cast(unsigned, b); }
; __device__ __forceinline__ float silu_f(float x) { return x * fast_sigmoid(x); }
; template <class Epi, class Sched, bool ALIGN_EPI = false, bool SP2 = false>
; __device__ __forceinline__ void gemm_phase(PG8_LAS unsigned char* lds, const Gemm g, const Sched& S, const Epi& E, const int wid) {
;     ...
;         if (!has_next) break;
; #pragma unroll
;         for (int a = 0; a < 2; ++a)
; #pragma unroll
;             for (int b = 0; b < 2; ++b)
; #pragma unroll
;                 for (int m = 0; m < 4; ++m)
; #pragma unroll
;                     for (int n = 0; n < 2; ++n) acc[a][b][m][n] = (f32x4){0.f, 0.f, 0.f, 0.f};
;         cur = nxt; cA = nA; cB = nB; ++ui;
;         if constexpr (ALIGN_EPI) { if (wr == 1) PG8_BAR; }
;     __device__ __forceinline__ void operator()(const f32x4 (&acc)[2][2][4][2], const pg8::Unit& u, int wr, int wc, int fr, int fq) const {
;     ...
; #pragma unroll
;         for (int ai = 0; ai < 2; ++ai)
; #pragma unroll
;             for (int m = 0; m < 4; ++m) {
;                 bf16_t* rowp = O + (size_t)(row0 + ai * 128 + m * 16) * ldc + col0;
;                 const f32x4 a0 = acc[ai][0][m][0], a1 = acc[ai][0][m][1], b0 = acc[ai][1][m][0], b1 = acc[ai][1][m][1];
;                 u32x4 w;
;                 w.x = pk2(silu_f(a0[0]) * b0[0], silu_f(a0[1]) * b0[1]); w.y = pk2(silu_f(a0[2]) * b0[2], silu_f(a0[3]) * b0[3]);
;                 w.z = pk2(silu_f(a1[0]) * b1[0], silu_f(a1[1]) * b1[1]); w.w = pk2(silu_f(a1[2]) * b1[2], silu_f(a1[3]) * b1[3]);
;                 *(u32x4*)rowp = w;
;             }
	v_rcp_f32_e32 v44, v44
	v_rcp_f32_e32 v45, v45
	v_pk_mul_f32 v[36:37], v[36:37], v[42:43]
	v_cvt_pk_bf16_f32 v59, v48, v49
	v_mad_i64_i32 v[64:65], s[22:23], v64, s44, v[146:147]
	v_lshl_add_u64 v[64:65], v[64:65], 0, v[144:145]
	global_store_dwordx4 v[64:65], v[56:59], off nt
	v_pk_mul_f32 v[32:33], v[36:37], v[32:33]
	v_mul_f32_e32 v36, 0xbfb8aa3b, v30
	v_cvt_pk_bf16_f32 v42, v32, v33
	v_pk_mul_f32 v[32:33], v[38:39], v[44:45]
	v_mul_f32_e32 v37, 0xbfb8aa3b, v31
	v_pk_mul_f32 v[32:33], v[32:33], v[34:35]
	v_mul_f32_e32 v34, 0xbfb8aa3b, v28
	v_mul_f32_e32 v35, 0xbfb8aa3b, v29
	v_exp_f32_e32 v34, v34
	v_exp_f32_e32 v35, v35
	v_exp_f32_e32 v36, v36
	v_exp_f32_e32 v37, v37
	v_add_f32_e32 v34, 1.0, v34
	v_add_f32_e32 v35, 1.0, v35
	v_rcp_f32_e32 v34, v34
	v_rcp_f32_e32 v35, v35
	v_add_f32_e32 v36, 1.0, v36
	v_add_f32_e32 v37, 1.0, v37
	v_rcp_f32_e32 v36, v36
	v_rcp_f32_e32 v37, v37
	v_pk_mul_f32 v[28:29], v[28:29], v[34:35]
	v_add_u32_e32 v48, 0x90, v154
	v_pk_mul_f32 v[24:25], v[28:29], v[24:25]
	v_pk_mul_f32 v[28:29], v[30:31], v[36:37]
	v_cvt_pk_bf16_f32 v24, v24, v25
	v_mul_f32_e32 v25, 0xbfb8aa3b, v20
	v_pk_mul_f32 v[26:27], v[28:29], v[26:27]
	v_exp_f32_e32 v28, v25
	v_mul_f32_e32 v25, 0xbfb8aa3b, v21
	v_exp_f32_e32 v29, v25
	v_cvt_pk_bf16_f32 v25, v26, v27
	v_add_f32_e32 v26, 1.0, v28
	v_mul_f32_e32 v28, 0xbfb8aa3b, v22
	v_add_f32_e32 v27, 1.0, v29
	v_mul_f32_e32 v29, 0xbfb8aa3b, v23
	v_exp_f32_e32 v28, v28
	v_exp_f32_e32 v29, v29
	v_rcp_f32_e32 v26, v26
	v_rcp_f32_e32 v27, v27
	v_add_f32_e32 v28, 1.0, v28
	v_add_f32_e32 v29, 1.0, v29
	v_rcp_f32_e32 v28, v28
	v_rcp_f32_e32 v29, v29
	v_pk_mul_f32 v[20:21], v[20:21], v[26:27]
	v_cvt_pk_bf16_f32 v43, v32, v33
	v_mad_i64_i32 v[48:49], s[22:23], v48, s44, v[146:147]
	v_lshl_add_u64 v[48:49], v[48:49], 0, v[144:145]
	global_store_dwordx4 v[48:49], v[40:43], off nt
	v_pk_mul_f32 v[16:17], v[20:21], v[16:17]
	v_mul_f32_e32 v20, 0xbfb8aa3b, v14
	v_cvt_pk_bf16_f32 v26, v16, v17
	v_pk_mul_f32 v[16:17], v[22:23], v[28:29]
	v_mul_f32_e32 v21, 0xbfb8aa3b, v15
	v_pk_mul_f32 v[16:17], v[16:17], v[18:19]
	v_mul_f32_e32 v18, 0xbfb8aa3b, v12
	v_mul_f32_e32 v19, 0xbfb8aa3b, v13
	v_exp_f32_e32 v18, v18
	v_exp_f32_e32 v19, v19
	v_exp_f32_e32 v20, v20
	v_exp_f32_e32 v21, v21
	v_add_f32_e32 v18, 1.0, v18
	v_add_f32_e32 v19, 1.0, v19
	v_rcp_f32_e32 v18, v18
	v_rcp_f32_e32 v19, v19
	v_add_f32_e32 v20, 1.0, v20
	v_add_f32_e32 v21, 1.0, v21
	v_rcp_f32_e32 v20, v20
	v_rcp_f32_e32 v21, v21
	v_pk_mul_f32 v[12:13], v[12:13], v[18:19]
	v_add_u32_e32 v32, 0xa0, v154
	v_pk_mul_f32 v[8:9], v[12:13], v[8:9]
	v_pk_mul_f32 v[12:13], v[14:15], v[20:21]
	v_cvt_pk_bf16_f32 v8, v8, v9
	v_mul_f32_e32 v9, 0xbfb8aa3b, v4
	v_pk_mul_f32 v[10:11], v[12:13], v[10:11]
	v_exp_f32_e32 v12, v9
	v_mul_f32_e32 v9, 0xbfb8aa3b, v5
	v_exp_f32_e32 v13, v9
	v_cvt_pk_bf16_f32 v9, v10, v11
	v_add_f32_e32 v10, 1.0, v12
	v_mul_f32_e32 v12, 0xbfb8aa3b, v6
	v_add_f32_e32 v11, 1.0, v13
	v_mul_f32_e32 v13, 0xbfb8aa3b, v7
	v_exp_f32_e32 v12, v12
	v_exp_f32_e32 v13, v13
	v_rcp_f32_e32 v10, v10
	v_rcp_f32_e32 v11, v11
	v_add_f32_e32 v12, 1.0, v12
	v_add_f32_e32 v13, 1.0, v13
	v_rcp_f32_e32 v12, v12
	v_rcp_f32_e32 v13, v13
	v_pk_mul_f32 v[4:5], v[4:5], v[10:11]
	v_cvt_pk_bf16_f32 v27, v16, v17
	v_mad_i64_i32 v[32:33], s[22:23], v32, s44, v[146:147]
	v_lshl_add_u64 v[32:33], v[32:33], 0, v[144:145]
	global_store_dwordx4 v[32:33], v[24:27], off nt
	v_pk_mul_f32 v[0:1], v[4:5], v[0:1]
	v_add_u32_e32 v16, 0xb0, v154
	v_cvt_pk_bf16_f32 v10, v0, v1
	v_pk_mul_f32 v[0:1], v[6:7], v[12:13]
	v_pk_mul_f32 v[0:1], v[0:1], v[2:3]
	v_cvt_pk_bf16_f32 v11, v0, v1
	v_mad_i64_i32 v[16:17], s[22:23], v16, s44, v[146:147]
	v_lshl_add_u64 v[16:17], v[16:17], 0, v[144:145]
	global_store_dwordx4 v[16:17], v[8:11], off nt
	s_andn2_b64 vcc, exec, s[6:7]
	s_mov_b64 s[6:7], -1
	s_cbranch_vccnz .LBB0_1307
	s_andn2_b64 vcc, exec, s[0:1]
	s_cbranch_vccnz .LBB0_1306
	s_barrier
	s_branch .LBB0_1306
